# FFN-in and hyena-in epilogue stores: 32-bit row*pitch+col offset with scalar base (saddr) instead of 64-bit v_mad_i64 + v_lshl_add_u64 per row
# baseline (speedup 1.0000x reference)
; __device__ __forceinline__ unsigned cvt_pk_bf16(float lo, float hi) { unsigned r; asm volatile("v_cvt_pk_bf16_f32 %0, %1, %2" : "=v"(r) : "v"(lo), "v"(hi)); return r; }
;     __device__ __forceinline__ void operator()(const f32x4 (&acc)[2][2][4][2], const Unit& u, int wr, int wc, int fr, int fq) const {
;         const int row0 = u.pm * BM + wr * 64 + fr, col0 = u.pn * HALF + wc * 32 + 8 * fq;
;         float rsv[2][4]; row_rs8(rsv, part, row0, fq);
; #pragma unroll
;         for (int ai = 0; ai < 2; ++ai)
; #pragma unroll
;             for (int m = 0; m < 4; ++m) { const int row = row0 + ai * HALF + m * 16; const float rs = rsv[ai][m], c1 = rs * -1.4426950408889634f, rs2 = rs * rs;
;                 u32x4 w;
; #pragma unroll
;                 for (int n = 0; n < 2; ++n)
; #pragma unroll
;                     for (int h = 0; h < 2; ++h) { const f32x2 g = (f32x2){acc[ai][0][m][n][2 * h], acc[ai][0][m][n][2 * h + 1]}, up = (f32x2){acc[ai][1][m][n][2 * h], acc[ai][1][m][n][2 * h + 1]};
;                         const f32x2 t = g * c1; f32x2 d = (f32x2){__builtin_amdgcn_exp2f(t[0]), __builtin_amdgcn_exp2f(t[1])} + 1.0f;
;                         const f32x2 r = (f32x2){__builtin_amdgcn_rcpf(d[0]), __builtin_amdgcn_rcpf(d[1])}; const f32x2 o = (g * up) * (r * rs2);
;                         w[2 * n + h] = cvt_pk_bf16(o[0], o[1]); }
;                 __builtin_nontemporal_store(w, (u32x4*)(H + (size_t)row * ldh + col0)); }
.LBB0_201:
	v_lshl_add_u32 v178, s59, 8, v190
	v_lshlrev_b32_e32 v194, 2, v190
	v_add_u32_e32 v194, 0x20000, v194
	ds_read_b32 v171, v194
	ds_read_b32 v165, v194 offset:64
	ds_read_b32 v145, v194 offset:128
	ds_read_b32 v144, v194 offset:192
	ds_read_b32 v137, v194 offset:512
	ds_read_b32 v136, v194 offset:576
	ds_read_b32 v129, v194 offset:640
	ds_read_b32 v128, v194 offset:704
	v_or_b32_e32 v176, 16, v178
	v_or_b32_e32 v174, 32, v178
	v_or_b32_e32 v172, 48, v178
	v_add_u32_e32 v170, 0x80, v178
	v_add_u32_e32 v168, 0x90, v178
	v_add_u32_e32 v166, 0xa0, v178
	v_add_u32_e32 v164, 0xb0, v178
	v_lshl_or_b32 v186, s3, 7, v192
	v_ashrrev_i32_e32 v187, 31, v186
	v_pk_mul_f32 v[120:121], v[124:125], v[120:121]
	v_pk_mul_f32 v[122:123], v[126:127], v[122:123]
	v_pk_mul_f32 v[118:119], v[114:115], v[118:119]
	v_pk_mul_f32 v[104:105], v[108:109], v[104:105]
	v_pk_mul_f32 v[106:107], v[110:111], v[106:107]
	v_pk_mul_f32 v[102:103], v[98:99], v[102:103]
	v_pk_mul_f32 v[88:89], v[92:93], v[88:89]
	v_pk_mul_f32 v[90:91], v[94:95], v[90:91]
	v_pk_mul_f32 v[86:87], v[82:83], v[86:87]
	v_pk_mul_f32 v[72:73], v[76:77], v[72:73]
	v_pk_mul_f32 v[74:75], v[78:79], v[74:75]
	v_pk_mul_f32 v[70:71], v[66:67], v[70:71]
	v_pk_mul_f32 v[56:57], v[60:61], v[56:57]
	v_pk_mul_f32 v[58:59], v[62:63], v[58:59]
	v_pk_mul_f32 v[54:55], v[50:51], v[54:55]
	v_pk_mul_f32 v[40:41], v[44:45], v[40:41]
	v_pk_mul_f32 v[42:43], v[46:47], v[42:43]
	v_pk_mul_f32 v[38:39], v[34:35], v[38:39]
	v_pk_mul_f32 v[24:25], v[28:29], v[24:25]
	v_pk_mul_f32 v[26:27], v[30:31], v[26:27]
	v_pk_mul_f32 v[22:23], v[18:19], v[22:23]
	v_pk_mul_f32 v[8:9], v[12:13], v[8:9]
	v_pk_mul_f32 v[10:11], v[14:15], v[10:11]
	v_pk_mul_f32 v[0:1], v[4:5], v[0:1]
	v_pk_mul_f32 v[2:3], v[6:7], v[2:3]
	s_waitcnt lgkmcnt(0)
	s_andn2_b64 vcc, exec, s[4:5]
	v_lshlrev_b32_e32 v226, 1, v186
	v_mul_f32_e32 v216, 0xbfb8aa3b, v171
	v_mul_f32_e32 v218, v171, v171
	v_pk_mul_f32 v[194:195], v[124:125], v[216:217] op_sel_hi:[1,0]
	v_pk_mul_f32 v[196:197], v[126:127], v[216:217] op_sel_hi:[1,0]
	v_pk_mul_f32 v[198:199], v[112:113], v[216:217] op_sel_hi:[1,0]
	v_pk_mul_f32 v[200:201], v[114:115], v[216:217] op_sel_hi:[1,0]
	v_pk_mul_f32 v[116:117], v[112:113], v[116:117]
	v_exp_f32_e32 v194, v194
	v_exp_f32_e32 v195, v195
	v_exp_f32_e32 v196, v196
	v_exp_f32_e32 v197, v197
	v_exp_f32_e32 v198, v198
	v_exp_f32_e32 v199, v199
	v_exp_f32_e32 v200, v200
	v_exp_f32_e32 v201, v201
	v_pk_add_f32 v[194:195], v[194:195], 1.0 op_sel_hi:[1,0]
	v_pk_add_f32 v[196:197], v[196:197], 1.0 op_sel_hi:[1,0]
	v_pk_add_f32 v[198:199], v[198:199], 1.0 op_sel_hi:[1,0]
	v_pk_add_f32 v[200:201], v[200:201], 1.0 op_sel_hi:[1,0]
	v_rcp_f32_e32 v194, v194
	v_rcp_f32_e32 v195, v195
	v_rcp_f32_e32 v196, v196
	v_rcp_f32_e32 v197, v197
	v_rcp_f32_e32 v198, v198
	v_rcp_f32_e32 v199, v199
	v_rcp_f32_e32 v200, v200
	v_rcp_f32_e32 v201, v201
	v_pk_mul_f32 v[194:195], v[218:219], v[194:195] op_sel_hi:[0,1]
	v_pk_mul_f32 v[196:197], v[218:219], v[196:197] op_sel_hi:[0,1]
	v_pk_mul_f32 v[198:199], v[218:219], v[198:199] op_sel_hi:[0,1]
	v_pk_mul_f32 v[200:201], v[218:219], v[200:201] op_sel_hi:[0,1]
	v_pk_mul_f32 v[120:121], v[120:121], v[194:195]
	v_pk_mul_f32 v[122:123], v[122:123], v[196:197]
	v_pk_mul_f32 v[116:117], v[116:117], v[198:199]
	v_pk_mul_f32 v[118:119], v[118:119], v[200:201]
	v_mad_u32_u24 v230, v178, s25, v226
	v_cvt_pk_bf16_f32 v120, v120, v121
	v_cvt_pk_bf16_f32 v121, v122, v123
	v_cvt_pk_bf16_f32 v122, v116, v117
	v_cvt_pk_bf16_f32 v123, v118, v119
	global_store_dwordx4 v230, v[120:123], s[10:11] nt
	v_mul_f32_e32 v216, 0xbfb8aa3b, v165
	v_mul_f32_e32 v218, v165, v165
	v_pk_mul_f32 v[194:195], v[108:109], v[216:217] op_sel_hi:[1,0]
	v_pk_mul_f32 v[196:197], v[110:111], v[216:217] op_sel_hi:[1,0]
	v_pk_mul_f32 v[198:199], v[96:97], v[216:217] op_sel_hi:[1,0]
	v_pk_mul_f32 v[200:201], v[98:99], v[216:217] op_sel_hi:[1,0]
	v_pk_mul_f32 v[100:101], v[96:97], v[100:101]
	v_exp_f32_e32 v194, v194
	v_exp_f32_e32 v195, v195
	v_exp_f32_e32 v196, v196
	v_exp_f32_e32 v197, v197
	v_exp_f32_e32 v198, v198
	v_exp_f32_e32 v199, v199
	v_exp_f32_e32 v200, v200
	v_exp_f32_e32 v201, v201
	v_pk_add_f32 v[194:195], v[194:195], 1.0 op_sel_hi:[1,0]
	v_pk_add_f32 v[196:197], v[196:197], 1.0 op_sel_hi:[1,0]
	v_pk_add_f32 v[198:199], v[198:199], 1.0 op_sel_hi:[1,0]
	v_pk_add_f32 v[200:201], v[200:201], 1.0 op_sel_hi:[1,0]
	v_rcp_f32_e32 v194, v194
	v_rcp_f32_e32 v195, v195
	v_rcp_f32_e32 v196, v196
	v_rcp_f32_e32 v197, v197
	v_rcp_f32_e32 v198, v198
	v_rcp_f32_e32 v199, v199
	v_rcp_f32_e32 v200, v200
	v_rcp_f32_e32 v201, v201
	v_pk_mul_f32 v[194:195], v[218:219], v[194:195] op_sel_hi:[0,1]
	v_pk_mul_f32 v[196:197], v[218:219], v[196:197] op_sel_hi:[0,1]
	v_pk_mul_f32 v[198:199], v[218:219], v[198:199] op_sel_hi:[0,1]
	v_pk_mul_f32 v[200:201], v[218:219], v[200:201] op_sel_hi:[0,1]
	v_pk_mul_f32 v[104:105], v[104:105], v[194:195]
	v_pk_mul_f32 v[106:107], v[106:107], v[196:197]
	v_pk_mul_f32 v[100:101], v[100:101], v[198:199]
	v_pk_mul_f32 v[102:103], v[102:103], v[200:201]
	v_mad_u32_u24 v230, v176, s25, v226
	v_cvt_pk_bf16_f32 v104, v104, v105
	v_cvt_pk_bf16_f32 v105, v106, v107
	v_cvt_pk_bf16_f32 v106, v100, v101
	v_cvt_pk_bf16_f32 v107, v102, v103
	global_store_dwordx4 v230, v[104:107], s[10:11] nt
	v_mul_f32_e32 v216, 0xbfb8aa3b, v145
	v_mul_f32_e32 v218, v145, v145
	v_pk_mul_f32 v[194:195], v[92:93], v[216:217] op_sel_hi:[1,0]
	v_pk_mul_f32 v[196:197], v[94:95], v[216:217] op_sel_hi:[1,0]
	v_pk_mul_f32 v[198:199], v[80:81], v[216:217] op_sel_hi:[1,0]
	v_pk_mul_f32 v[200:201], v[82:83], v[216:217] op_sel_hi:[1,0]
	v_pk_mul_f32 v[84:85], v[80:81], v[84:85]
; __device__ __forceinline__ unsigned cvt_pk_bf16(float lo, float hi) { unsigned r; asm volatile("v_cvt_pk_bf16_f32 %0, %1, %2" : "=v"(r) : "v"(lo), "v"(hi)); return r; }
;     __device__ __forceinline__ void operator()(const f32x4 (&acc)[2][2][4][2], const Unit& u, int wr, int wc, int fr, int fq) const {
;     ...
;             for (int m = 0; m < 4; ++m) { const int row = row0 + ai * HALF + m * 16; const float rs = rsv[ai][m], c1 = rs * -1.4426950408889634f, rs2 = rs * rs;
;                 u32x4 w;
; #pragma unroll
;                 for (int n = 0; n < 2; ++n)
; #pragma unroll
;                     for (int h = 0; h < 2; ++h) { const f32x2 g = (f32x2){acc[ai][0][m][n][2 * h], acc[ai][0][m][n][2 * h + 1]}, up = (f32x2){acc[ai][1][m][n][2 * h], acc[ai][1][m][n][2 * h + 1]};
;                         const f32x2 t = g * c1; f32x2 d = (f32x2){__builtin_amdgcn_exp2f(t[0]), __builtin_amdgcn_exp2f(t[1])} + 1.0f;
;                         const f32x2 r = (f32x2){__builtin_amdgcn_rcpf(d[0]), __builtin_amdgcn_rcpf(d[1])}; const f32x2 o = (g * up) * (r * rs2);
;                         w[2 * n + h] = cvt_pk_bf16(o[0], o[1]); }
;                 __builtin_nontemporal_store(w, (u32x4*)(H + (size_t)row * ldh + col0)); }
	v_exp_f32_e32 v194, v194
	v_exp_f32_e32 v195, v195
	v_exp_f32_e32 v196, v196
	v_exp_f32_e32 v197, v197
	v_exp_f32_e32 v198, v198
	v_exp_f32_e32 v199, v199
	v_exp_f32_e32 v200, v200
	v_exp_f32_e32 v201, v201
	v_pk_add_f32 v[194:195], v[194:195], 1.0 op_sel_hi:[1,0]
	v_pk_add_f32 v[196:197], v[196:197], 1.0 op_sel_hi:[1,0]
	v_pk_add_f32 v[198:199], v[198:199], 1.0 op_sel_hi:[1,0]
	v_pk_add_f32 v[200:201], v[200:201], 1.0 op_sel_hi:[1,0]
	v_rcp_f32_e32 v194, v194
	v_rcp_f32_e32 v195, v195
	v_rcp_f32_e32 v196, v196
	v_rcp_f32_e32 v197, v197
	v_rcp_f32_e32 v198, v198
	v_rcp_f32_e32 v199, v199
	v_rcp_f32_e32 v200, v200
	v_rcp_f32_e32 v201, v201
	v_pk_mul_f32 v[194:195], v[218:219], v[194:195] op_sel_hi:[0,1]
	v_pk_mul_f32 v[196:197], v[218:219], v[196:197] op_sel_hi:[0,1]
	v_pk_mul_f32 v[198:199], v[218:219], v[198:199] op_sel_hi:[0,1]
	v_pk_mul_f32 v[200:201], v[218:219], v[200:201] op_sel_hi:[0,1]
	v_pk_mul_f32 v[88:89], v[88:89], v[194:195]
	v_pk_mul_f32 v[90:91], v[90:91], v[196:197]
	v_pk_mul_f32 v[84:85], v[84:85], v[198:199]
	v_pk_mul_f32 v[86:87], v[86:87], v[200:201]
	v_mad_u32_u24 v230, v174, s25, v226
	v_cvt_pk_bf16_f32 v88, v88, v89
	v_cvt_pk_bf16_f32 v89, v90, v91
	v_cvt_pk_bf16_f32 v90, v84, v85
	v_cvt_pk_bf16_f32 v91, v86, v87
	global_store_dwordx4 v230, v[88:91], s[10:11] nt
	v_mul_f32_e32 v216, 0xbfb8aa3b, v144
	v_mul_f32_e32 v218, v144, v144
	v_pk_mul_f32 v[194:195], v[76:77], v[216:217] op_sel_hi:[1,0]
	v_pk_mul_f32 v[196:197], v[78:79], v[216:217] op_sel_hi:[1,0]
	v_pk_mul_f32 v[198:199], v[64:65], v[216:217] op_sel_hi:[1,0]
	v_pk_mul_f32 v[200:201], v[66:67], v[216:217] op_sel_hi:[1,0]
	v_pk_mul_f32 v[68:69], v[64:65], v[68:69]
	v_exp_f32_e32 v194, v194
	v_exp_f32_e32 v195, v195
	v_exp_f32_e32 v196, v196
	v_exp_f32_e32 v197, v197
	v_exp_f32_e32 v198, v198
	v_exp_f32_e32 v199, v199
	v_exp_f32_e32 v200, v200
	v_exp_f32_e32 v201, v201
	v_pk_add_f32 v[194:195], v[194:195], 1.0 op_sel_hi:[1,0]
	v_pk_add_f32 v[196:197], v[196:197], 1.0 op_sel_hi:[1,0]
	v_pk_add_f32 v[198:199], v[198:199], 1.0 op_sel_hi:[1,0]
	v_pk_add_f32 v[200:201], v[200:201], 1.0 op_sel_hi:[1,0]
	v_rcp_f32_e32 v194, v194
	v_rcp_f32_e32 v195, v195
	v_rcp_f32_e32 v196, v196
	v_rcp_f32_e32 v197, v197
	v_rcp_f32_e32 v198, v198
	v_rcp_f32_e32 v199, v199
	v_rcp_f32_e32 v200, v200
	v_rcp_f32_e32 v201, v201
	v_pk_mul_f32 v[194:195], v[218:219], v[194:195] op_sel_hi:[0,1]
	v_pk_mul_f32 v[196:197], v[218:219], v[196:197] op_sel_hi:[0,1]
	v_pk_mul_f32 v[198:199], v[218:219], v[198:199] op_sel_hi:[0,1]
	v_pk_mul_f32 v[200:201], v[218:219], v[200:201] op_sel_hi:[0,1]
	v_pk_mul_f32 v[72:73], v[72:73], v[194:195]
	v_pk_mul_f32 v[74:75], v[74:75], v[196:197]
	v_pk_mul_f32 v[68:69], v[68:69], v[198:199]
	v_pk_mul_f32 v[70:71], v[70:71], v[200:201]
	v_mad_u32_u24 v230, v172, s25, v226
	v_cvt_pk_bf16_f32 v72, v72, v73
	v_cvt_pk_bf16_f32 v73, v74, v75
	v_cvt_pk_bf16_f32 v74, v68, v69
	v_cvt_pk_bf16_f32 v75, v70, v71
	global_store_dwordx4 v230, v[72:75], s[10:11] nt
	v_mul_f32_e32 v216, 0xbfb8aa3b, v137
	v_mul_f32_e32 v218, v137, v137
	v_pk_mul_f32 v[194:195], v[60:61], v[216:217] op_sel_hi:[1,0]
	v_pk_mul_f32 v[196:197], v[62:63], v[216:217] op_sel_hi:[1,0]
	v_pk_mul_f32 v[198:199], v[48:49], v[216:217] op_sel_hi:[1,0]
	v_pk_mul_f32 v[200:201], v[50:51], v[216:217] op_sel_hi:[1,0]
	v_pk_mul_f32 v[52:53], v[48:49], v[52:53]
	v_exp_f32_e32 v194, v194
	v_exp_f32_e32 v195, v195
	v_exp_f32_e32 v196, v196
	v_exp_f32_e32 v197, v197
	v_exp_f32_e32 v198, v198
	v_exp_f32_e32 v199, v199
	v_exp_f32_e32 v200, v200
	v_exp_f32_e32 v201, v201
	v_pk_add_f32 v[194:195], v[194:195], 1.0 op_sel_hi:[1,0]
	v_pk_add_f32 v[196:197], v[196:197], 1.0 op_sel_hi:[1,0]
	v_pk_add_f32 v[198:199], v[198:199], 1.0 op_sel_hi:[1,0]
	v_pk_add_f32 v[200:201], v[200:201], 1.0 op_sel_hi:[1,0]
	v_rcp_f32_e32 v194, v194
	v_rcp_f32_e32 v195, v195
	v_rcp_f32_e32 v196, v196
	v_rcp_f32_e32 v197, v197
	v_rcp_f32_e32 v198, v198
	v_rcp_f32_e32 v199, v199
	v_rcp_f32_e32 v200, v200
	v_rcp_f32_e32 v201, v201
	v_pk_mul_f32 v[194:195], v[218:219], v[194:195] op_sel_hi:[0,1]
	v_pk_mul_f32 v[196:197], v[218:219], v[196:197] op_sel_hi:[0,1]
	v_pk_mul_f32 v[198:199], v[218:219], v[198:199] op_sel_hi:[0,1]
	v_pk_mul_f32 v[200:201], v[218:219], v[200:201] op_sel_hi:[0,1]
	v_pk_mul_f32 v[56:57], v[56:57], v[194:195]
	v_pk_mul_f32 v[58:59], v[58:59], v[196:197]
	v_pk_mul_f32 v[52:53], v[52:53], v[198:199]
	v_pk_mul_f32 v[54:55], v[54:55], v[200:201]
	v_mad_u32_u24 v230, v170, s25, v226
	v_cvt_pk_bf16_f32 v56, v56, v57
	v_cvt_pk_bf16_f32 v57, v58, v59
	v_cvt_pk_bf16_f32 v58, v52, v53
	v_cvt_pk_bf16_f32 v59, v54, v55
	global_store_dwordx4 v230, v[56:59], s[10:11] nt
	v_mul_f32_e32 v216, 0xbfb8aa3b, v136
	v_mul_f32_e32 v218, v136, v136
	v_pk_mul_f32 v[194:195], v[44:45], v[216:217] op_sel_hi:[1,0]
	v_pk_mul_f32 v[196:197], v[46:47], v[216:217] op_sel_hi:[1,0]
; __device__ __forceinline__ unsigned cvt_pk_bf16(float lo, float hi) { unsigned r; asm volatile("v_cvt_pk_bf16_f32 %0, %1, %2" : "=v"(r) : "v"(lo), "v"(hi)); return r; }
;     __device__ __forceinline__ void operator()(const f32x4 (&acc)[2][2][4][2], const Unit& u, int wr, int wc, int fr, int fq) const {
;     ...
;             for (int m = 0; m < 4; ++m) { const int row = row0 + ai * HALF + m * 16; const float rs = rsv[ai][m], c1 = rs * -1.4426950408889634f, rs2 = rs * rs;
;                 u32x4 w;
; #pragma unroll
;                 for (int n = 0; n < 2; ++n)
; #pragma unroll
;                     for (int h = 0; h < 2; ++h) { const f32x2 g = (f32x2){acc[ai][0][m][n][2 * h], acc[ai][0][m][n][2 * h + 1]}, up = (f32x2){acc[ai][1][m][n][2 * h], acc[ai][1][m][n][2 * h + 1]};
;                         const f32x2 t = g * c1; f32x2 d = (f32x2){__builtin_amdgcn_exp2f(t[0]), __builtin_amdgcn_exp2f(t[1])} + 1.0f;
;                         const f32x2 r = (f32x2){__builtin_amdgcn_rcpf(d[0]), __builtin_amdgcn_rcpf(d[1])}; const f32x2 o = (g * up) * (r * rs2);
;                         w[2 * n + h] = cvt_pk_bf16(o[0], o[1]); }
;                 __builtin_nontemporal_store(w, (u32x4*)(H + (size_t)row * ldh + col0)); }
	v_pk_mul_f32 v[198:199], v[32:33], v[216:217] op_sel_hi:[1,0]
	v_pk_mul_f32 v[200:201], v[34:35], v[216:217] op_sel_hi:[1,0]
	v_pk_mul_f32 v[36:37], v[32:33], v[36:37]
	v_exp_f32_e32 v194, v194
	v_exp_f32_e32 v195, v195
	v_exp_f32_e32 v196, v196
	v_exp_f32_e32 v197, v197
	v_exp_f32_e32 v198, v198
	v_exp_f32_e32 v199, v199
	v_exp_f32_e32 v200, v200
	v_exp_f32_e32 v201, v201
	v_pk_add_f32 v[194:195], v[194:195], 1.0 op_sel_hi:[1,0]
	v_pk_add_f32 v[196:197], v[196:197], 1.0 op_sel_hi:[1,0]
	v_pk_add_f32 v[198:199], v[198:199], 1.0 op_sel_hi:[1,0]
	v_pk_add_f32 v[200:201], v[200:201], 1.0 op_sel_hi:[1,0]
	v_rcp_f32_e32 v194, v194
	v_rcp_f32_e32 v195, v195
	v_rcp_f32_e32 v196, v196
	v_rcp_f32_e32 v197, v197
	v_rcp_f32_e32 v198, v198
	v_rcp_f32_e32 v199, v199
	v_rcp_f32_e32 v200, v200
	v_rcp_f32_e32 v201, v201
	v_pk_mul_f32 v[194:195], v[218:219], v[194:195] op_sel_hi:[0,1]
	v_pk_mul_f32 v[196:197], v[218:219], v[196:197] op_sel_hi:[0,1]
	v_pk_mul_f32 v[198:199], v[218:219], v[198:199] op_sel_hi:[0,1]
	v_pk_mul_f32 v[200:201], v[218:219], v[200:201] op_sel_hi:[0,1]
	v_pk_mul_f32 v[40:41], v[40:41], v[194:195]
	v_pk_mul_f32 v[42:43], v[42:43], v[196:197]
	v_pk_mul_f32 v[36:37], v[36:37], v[198:199]
	v_pk_mul_f32 v[38:39], v[38:39], v[200:201]
	v_mad_u32_u24 v230, v168, s25, v226
	v_cvt_pk_bf16_f32 v40, v40, v41
	v_cvt_pk_bf16_f32 v41, v42, v43
	v_cvt_pk_bf16_f32 v42, v36, v37
	v_cvt_pk_bf16_f32 v43, v38, v39
	global_store_dwordx4 v230, v[40:43], s[10:11] nt
	v_mul_f32_e32 v216, 0xbfb8aa3b, v129
	v_mul_f32_e32 v218, v129, v129
	v_pk_mul_f32 v[194:195], v[28:29], v[216:217] op_sel_hi:[1,0]
	v_pk_mul_f32 v[196:197], v[30:31], v[216:217] op_sel_hi:[1,0]
	v_pk_mul_f32 v[198:199], v[16:17], v[216:217] op_sel_hi:[1,0]
	v_pk_mul_f32 v[200:201], v[18:19], v[216:217] op_sel_hi:[1,0]
	v_pk_mul_f32 v[20:21], v[16:17], v[20:21]
	v_exp_f32_e32 v194, v194
	v_exp_f32_e32 v195, v195
	v_exp_f32_e32 v196, v196
	v_exp_f32_e32 v197, v197
	v_exp_f32_e32 v198, v198
	v_exp_f32_e32 v199, v199
	v_exp_f32_e32 v200, v200
	v_exp_f32_e32 v201, v201
	v_pk_add_f32 v[194:195], v[194:195], 1.0 op_sel_hi:[1,0]
	v_pk_add_f32 v[196:197], v[196:197], 1.0 op_sel_hi:[1,0]
	v_pk_add_f32 v[198:199], v[198:199], 1.0 op_sel_hi:[1,0]
	v_pk_add_f32 v[200:201], v[200:201], 1.0 op_sel_hi:[1,0]
	v_rcp_f32_e32 v194, v194
	v_rcp_f32_e32 v195, v195
	v_rcp_f32_e32 v196, v196
	v_rcp_f32_e32 v197, v197
	v_rcp_f32_e32 v198, v198
	v_rcp_f32_e32 v199, v199
	v_rcp_f32_e32 v200, v200
	v_rcp_f32_e32 v201, v201
	v_pk_mul_f32 v[194:195], v[218:219], v[194:195] op_sel_hi:[0,1]
	v_pk_mul_f32 v[196:197], v[218:219], v[196:197] op_sel_hi:[0,1]
	v_pk_mul_f32 v[198:199], v[218:219], v[198:199] op_sel_hi:[0,1]
	v_pk_mul_f32 v[200:201], v[218:219], v[200:201] op_sel_hi:[0,1]
	v_pk_mul_f32 v[24:25], v[24:25], v[194:195]
	v_pk_mul_f32 v[26:27], v[26:27], v[196:197]
	v_pk_mul_f32 v[20:21], v[20:21], v[198:199]
	v_pk_mul_f32 v[22:23], v[22:23], v[200:201]
	v_mad_u32_u24 v230, v166, s25, v226
	v_cvt_pk_bf16_f32 v24, v24, v25
	v_cvt_pk_bf16_f32 v25, v26, v27
	v_cvt_pk_bf16_f32 v26, v20, v21
	v_cvt_pk_bf16_f32 v27, v22, v23
	global_store_dwordx4 v230, v[24:27], s[10:11] nt
	v_mul_f32_e32 v216, 0xbfb8aa3b, v128
	v_mul_f32_e32 v218, v128, v128
	v_pk_mul_f32 v[194:195], v[12:13], v[216:217] op_sel_hi:[1,0]
	v_pk_mul_f32 v[196:197], v[14:15], v[216:217] op_sel_hi:[1,0]
	v_pk_mul_f32 v[198:199], v[4:5], v[216:217] op_sel_hi:[1,0]
	v_pk_mul_f32 v[200:201], v[6:7], v[216:217] op_sel_hi:[1,0]
	v_exp_f32_e32 v194, v194
	v_exp_f32_e32 v195, v195
	v_exp_f32_e32 v196, v196
	v_exp_f32_e32 v197, v197
	v_exp_f32_e32 v198, v198
	v_exp_f32_e32 v199, v199
	v_exp_f32_e32 v200, v200
	v_exp_f32_e32 v201, v201
	v_pk_add_f32 v[194:195], v[194:195], 1.0 op_sel_hi:[1,0]
	v_pk_add_f32 v[196:197], v[196:197], 1.0 op_sel_hi:[1,0]
	v_pk_add_f32 v[198:199], v[198:199], 1.0 op_sel_hi:[1,0]
	v_pk_add_f32 v[200:201], v[200:201], 1.0 op_sel_hi:[1,0]
	v_rcp_f32_e32 v194, v194
	v_rcp_f32_e32 v195, v195
	v_rcp_f32_e32 v196, v196
	v_rcp_f32_e32 v197, v197
	v_rcp_f32_e32 v198, v198
	v_rcp_f32_e32 v199, v199
	v_rcp_f32_e32 v200, v200
	v_rcp_f32_e32 v201, v201
	v_pk_mul_f32 v[194:195], v[218:219], v[194:195] op_sel_hi:[0,1]
	v_pk_mul_f32 v[196:197], v[218:219], v[196:197] op_sel_hi:[0,1]
	v_pk_mul_f32 v[198:199], v[218:219], v[198:199] op_sel_hi:[0,1]
	v_pk_mul_f32 v[200:201], v[218:219], v[200:201] op_sel_hi:[0,1]
	v_pk_mul_f32 v[8:9], v[8:9], v[194:195]
	v_pk_mul_f32 v[10:11], v[10:11], v[196:197]
	v_pk_mul_f32 v[0:1], v[0:1], v[198:199]
	v_pk_mul_f32 v[2:3], v[2:3], v[200:201]
	v_mad_u32_u24 v230, v164, s25, v226
	v_cvt_pk_bf16_f32 v8, v8, v9
	v_cvt_pk_bf16_f32 v9, v10, v11
	v_cvt_pk_bf16_f32 v10, v0, v1
	v_cvt_pk_bf16_f32 v11, v2, v3
	s_mov_b64 s[6:7], -1
	global_store_dwordx4 v230, v[8:11], s[10:11] nt
	s_cbranch_vccnz .LBB0_194
	s_andn2_b64 vcc, exec, s[8:9]
	s_cbranch_vccnz .LBB0_193
	s_mov_b32 s96, 1
	s_branch .LBB0_193

; __device__ __forceinline__ unsigned cvt_pk_bf16(float lo, float hi) { unsigned r; asm volatile("v_cvt_pk_bf16_f32 %0, %1, %2" : "=v"(r) : "v"(lo), "v"(hi)); return r; }
;     __device__ __forceinline__ void operator()(const f32x4 (&acc)[2][2][4][2], const Unit& u, int wr, int wc, int fr, int fq) const {
;         const int row0 = u.pm * BM + wr * 64 + fr, col0 = u.pn * BM + wc * 32 + 8 * fq;
;         f32x4 bv[2][2];
; #pragma unroll
;         for (int bj = 0; bj < 2; ++bj)
; #pragma unroll
;             for (int n = 0; n < 2; ++n) bv[bj][n] = bias ? *(const f32x4*)(bias + col0 + bj * HALF + 4 * n) : (f32x4){0.f, 0.f, 0.f, 0.f};
;         float rsv[2][4]; row_rs8(rsv, part, row0, fq);
; #pragma unroll
;         for (int ai = 0; ai < 2; ++ai)
; #pragma unroll
;             for (int m = 0; m < 4; ++m) { const int row = row0 + ai * HALF + m * 16; const float rs = rsv[ai][m];
; #pragma unroll
;                 for (int bj = 0; bj < 2; ++bj) { const f32x4 v0 = acc[ai][bj][m][0] * rs + bv[bj][0], v1 = acc[ai][bj][m][1] * rs + bv[bj][1];
;                     u32x4 w; w.x = cvt_pk_bf16(v0[0], v0[1]); w.y = cvt_pk_bf16(v0[2], v0[3]); w.z = cvt_pk_bf16(v1[0], v1[1]); w.w = cvt_pk_bf16(v1[2], v1[3]);
;                     __builtin_nontemporal_store(w, (u32x4*)(O + (size_t)row * ldc + col0 + bj * HALF)); } }
.LBB0_371:
	v_lshl_add_u32 v202, s3, 8, v216
	v_lshlrev_b32_e32 v165, 2, v216
	v_add_u32_e32 v165, 0x20000, v165
	ds_read_b32 v146, v165
	ds_read_b32 v148, v165 offset:64
	ds_read_b32 v150, v165 offset:128
	ds_read_b32 v152, v165 offset:192
	ds_read_b32 v154, v165 offset:512
	ds_read_b32 v156, v165 offset:576
	ds_read_b32 v158, v165 offset:640
	ds_read_b32 v164, v165 offset:704
	v_lshlrev_b32_e32 v162, 1, v196
	s_andn2_b64 vcc, exec, s[6:7]
	s_waitcnt vmcnt(0)
	s_waitcnt lgkmcnt(0)
	v_mov_b32_e32 v200, v202
	v_mad_u32_u24 v166, v200, s30, v162
	v_pk_fma_f32 v[124:125], v[124:125], v[146:147], v[132:133] op_sel_hi:[1,0,1]
	v_pk_fma_f32 v[126:127], v[126:127], v[146:147], v[134:135] op_sel_hi:[1,0,1]
	v_pk_fma_f32 v[120:121], v[120:121], v[146:147], v[128:129] op_sel_hi:[1,0,1]
	v_pk_fma_f32 v[122:123], v[122:123], v[146:147], v[130:131] op_sel_hi:[1,0,1]
	v_cvt_pk_bf16_f32 v124, v124, v125
	v_cvt_pk_bf16_f32 v125, v126, v127
	v_cvt_pk_bf16_f32 v126, v120, v121
	v_cvt_pk_bf16_f32 v127, v122, v123
	global_store_dwordx4 v166, v[124:127], s[14:15] nt
	v_pk_fma_f32 v[116:117], v[116:117], v[146:147], v[140:141] op_sel_hi:[1,0,1]
	v_pk_fma_f32 v[118:119], v[118:119], v[146:147], v[142:143] op_sel_hi:[1,0,1]
	v_pk_fma_f32 v[108:109], v[108:109], v[146:147], v[136:137] op_sel_hi:[1,0,1]
	v_pk_fma_f32 v[110:111], v[110:111], v[146:147], v[138:139] op_sel_hi:[1,0,1]
	v_cvt_pk_bf16_f32 v116, v116, v117
	v_cvt_pk_bf16_f32 v117, v118, v119
	v_cvt_pk_bf16_f32 v118, v108, v109
	v_cvt_pk_bf16_f32 v119, v110, v111
	global_store_dwordx4 v166, v[116:119], s[14:15] offset:256 nt
	v_add_u32_e32 v200, 0x10, v202
	v_mad_u32_u24 v166, v200, s30, v162
	v_pk_fma_f32 v[112:113], v[112:113], v[148:149], v[132:133] op_sel_hi:[1,0,1]
	v_pk_fma_f32 v[114:115], v[114:115], v[148:149], v[134:135] op_sel_hi:[1,0,1]
	v_pk_fma_f32 v[104:105], v[104:105], v[148:149], v[128:129] op_sel_hi:[1,0,1]
	v_pk_fma_f32 v[106:107], v[106:107], v[148:149], v[130:131] op_sel_hi:[1,0,1]
	v_cvt_pk_bf16_f32 v112, v112, v113
	v_cvt_pk_bf16_f32 v113, v114, v115
	v_cvt_pk_bf16_f32 v114, v104, v105
	v_cvt_pk_bf16_f32 v115, v106, v107
	global_store_dwordx4 v166, v[112:115], s[14:15] nt
	v_pk_fma_f32 v[100:101], v[100:101], v[148:149], v[140:141] op_sel_hi:[1,0,1]
	v_pk_fma_f32 v[102:103], v[102:103], v[148:149], v[142:143] op_sel_hi:[1,0,1]
	v_pk_fma_f32 v[92:93], v[92:93], v[148:149], v[136:137] op_sel_hi:[1,0,1]
	v_pk_fma_f32 v[94:95], v[94:95], v[148:149], v[138:139] op_sel_hi:[1,0,1]
	v_cvt_pk_bf16_f32 v100, v100, v101
	v_cvt_pk_bf16_f32 v101, v102, v103
	v_cvt_pk_bf16_f32 v102, v92, v93
	v_cvt_pk_bf16_f32 v103, v94, v95
	global_store_dwordx4 v166, v[100:103], s[14:15] offset:256 nt
	v_add_u32_e32 v200, 0x20, v202
	v_mad_u32_u24 v166, v200, s30, v162
	v_pk_fma_f32 v[96:97], v[96:97], v[150:151], v[132:133] op_sel_hi:[1,0,1]
	v_pk_fma_f32 v[98:99], v[98:99], v[150:151], v[134:135] op_sel_hi:[1,0,1]
	v_pk_fma_f32 v[88:89], v[88:89], v[150:151], v[128:129] op_sel_hi:[1,0,1]
	v_pk_fma_f32 v[90:91], v[90:91], v[150:151], v[130:131] op_sel_hi:[1,0,1]
	v_cvt_pk_bf16_f32 v96, v96, v97
	v_cvt_pk_bf16_f32 v97, v98, v99
	v_cvt_pk_bf16_f32 v98, v88, v89
	v_cvt_pk_bf16_f32 v99, v90, v91
	global_store_dwordx4 v166, v[96:99], s[14:15] nt
	v_pk_fma_f32 v[84:85], v[84:85], v[150:151], v[140:141] op_sel_hi:[1,0,1]
	v_pk_fma_f32 v[86:87], v[86:87], v[150:151], v[142:143] op_sel_hi:[1,0,1]
	v_pk_fma_f32 v[76:77], v[76:77], v[150:151], v[136:137] op_sel_hi:[1,0,1]
	v_pk_fma_f32 v[78:79], v[78:79], v[150:151], v[138:139] op_sel_hi:[1,0,1]
	v_cvt_pk_bf16_f32 v84, v84, v85
	v_cvt_pk_bf16_f32 v85, v86, v87
	v_cvt_pk_bf16_f32 v86, v76, v77
	v_cvt_pk_bf16_f32 v87, v78, v79
	global_store_dwordx4 v166, v[84:87], s[14:15] offset:256 nt
	v_add_u32_e32 v200, 0x30, v202
	v_mad_u32_u24 v166, v200, s30, v162
	v_pk_fma_f32 v[80:81], v[80:81], v[152:153], v[132:133] op_sel_hi:[1,0,1]
	v_pk_fma_f32 v[82:83], v[82:83], v[152:153], v[134:135] op_sel_hi:[1,0,1]
	v_pk_fma_f32 v[72:73], v[72:73], v[152:153], v[128:129] op_sel_hi:[1,0,1]
	v_pk_fma_f32 v[74:75], v[74:75], v[152:153], v[130:131] op_sel_hi:[1,0,1]
	v_cvt_pk_bf16_f32 v80, v80, v81
	v_cvt_pk_bf16_f32 v81, v82, v83
	v_cvt_pk_bf16_f32 v82, v72, v73
	v_cvt_pk_bf16_f32 v83, v74, v75
	global_store_dwordx4 v166, v[80:83], s[14:15] nt
	v_pk_fma_f32 v[68:69], v[68:69], v[152:153], v[140:141] op_sel_hi:[1,0,1]
	v_pk_fma_f32 v[70:71], v[70:71], v[152:153], v[142:143] op_sel_hi:[1,0,1]
	v_pk_fma_f32 v[64:65], v[64:65], v[152:153], v[136:137] op_sel_hi:[1,0,1]
; __device__ __forceinline__ unsigned cvt_pk_bf16(float lo, float hi) { unsigned r; asm volatile("v_cvt_pk_bf16_f32 %0, %1, %2" : "=v"(r) : "v"(lo), "v"(hi)); return r; }
;     __device__ __forceinline__ void operator()(const f32x4 (&acc)[2][2][4][2], const Unit& u, int wr, int wc, int fr, int fq) const {
;     ...
;         for (int ai = 0; ai < 2; ++ai)
; #pragma unroll
;             for (int m = 0; m < 4; ++m) { const int row = row0 + ai * HALF + m * 16; const float rs = rsv[ai][m];
; #pragma unroll
;                 for (int bj = 0; bj < 2; ++bj) { const f32x4 v0 = acc[ai][bj][m][0] * rs + bv[bj][0], v1 = acc[ai][bj][m][1] * rs + bv[bj][1];
;                     u32x4 w; w.x = cvt_pk_bf16(v0[0], v0[1]); w.y = cvt_pk_bf16(v0[2], v0[3]); w.z = cvt_pk_bf16(v1[0], v1[1]); w.w = cvt_pk_bf16(v1[2], v1[3]);
;                     __builtin_nontemporal_store(w, (u32x4*)(O + (size_t)row * ldc + col0 + bj * HALF)); } }
	v_pk_fma_f32 v[66:67], v[66:67], v[152:153], v[138:139] op_sel_hi:[1,0,1]
	v_cvt_pk_bf16_f32 v68, v68, v69
	v_cvt_pk_bf16_f32 v69, v70, v71
	v_cvt_pk_bf16_f32 v70, v64, v65
	v_cvt_pk_bf16_f32 v71, v66, v67
	global_store_dwordx4 v166, v[68:71], s[14:15] offset:256 nt
	v_add_u32_e32 v200, 0x80, v202
	v_mad_u32_u24 v166, v200, s30, v162
	v_pk_fma_f32 v[60:61], v[60:61], v[154:155], v[132:133] op_sel_hi:[1,0,1]
	v_pk_fma_f32 v[62:63], v[62:63], v[154:155], v[134:135] op_sel_hi:[1,0,1]
	v_pk_fma_f32 v[56:57], v[56:57], v[154:155], v[128:129] op_sel_hi:[1,0,1]
	v_pk_fma_f32 v[58:59], v[58:59], v[154:155], v[130:131] op_sel_hi:[1,0,1]
	v_cvt_pk_bf16_f32 v60, v60, v61
	v_cvt_pk_bf16_f32 v61, v62, v63
	v_cvt_pk_bf16_f32 v62, v56, v57
	v_cvt_pk_bf16_f32 v63, v58, v59
	global_store_dwordx4 v166, v[60:63], s[14:15] nt
	v_pk_fma_f32 v[52:53], v[52:53], v[154:155], v[140:141] op_sel_hi:[1,0,1]
	v_pk_fma_f32 v[54:55], v[54:55], v[154:155], v[142:143] op_sel_hi:[1,0,1]
	v_pk_fma_f32 v[44:45], v[44:45], v[154:155], v[136:137] op_sel_hi:[1,0,1]
	v_pk_fma_f32 v[46:47], v[46:47], v[154:155], v[138:139] op_sel_hi:[1,0,1]
	v_cvt_pk_bf16_f32 v52, v52, v53
	v_cvt_pk_bf16_f32 v53, v54, v55
	v_cvt_pk_bf16_f32 v54, v44, v45
	v_cvt_pk_bf16_f32 v55, v46, v47
	global_store_dwordx4 v166, v[52:55], s[14:15] offset:256 nt
	v_add_u32_e32 v200, 0x90, v202
	v_mad_u32_u24 v166, v200, s30, v162
	v_pk_fma_f32 v[48:49], v[48:49], v[156:157], v[132:133] op_sel_hi:[1,0,1]
	v_pk_fma_f32 v[50:51], v[50:51], v[156:157], v[134:135] op_sel_hi:[1,0,1]
	v_pk_fma_f32 v[40:41], v[40:41], v[156:157], v[128:129] op_sel_hi:[1,0,1]
	v_pk_fma_f32 v[42:43], v[42:43], v[156:157], v[130:131] op_sel_hi:[1,0,1]
	v_cvt_pk_bf16_f32 v48, v48, v49
	v_cvt_pk_bf16_f32 v49, v50, v51
	v_cvt_pk_bf16_f32 v50, v40, v41
	v_cvt_pk_bf16_f32 v51, v42, v43
	global_store_dwordx4 v166, v[48:51], s[14:15] nt
	v_pk_fma_f32 v[36:37], v[36:37], v[156:157], v[140:141] op_sel_hi:[1,0,1]
	v_pk_fma_f32 v[38:39], v[38:39], v[156:157], v[142:143] op_sel_hi:[1,0,1]
	v_pk_fma_f32 v[28:29], v[28:29], v[156:157], v[136:137] op_sel_hi:[1,0,1]
	v_pk_fma_f32 v[30:31], v[30:31], v[156:157], v[138:139] op_sel_hi:[1,0,1]
	v_cvt_pk_bf16_f32 v36, v36, v37
	v_cvt_pk_bf16_f32 v37, v38, v39
	v_cvt_pk_bf16_f32 v38, v28, v29
	v_cvt_pk_bf16_f32 v39, v30, v31
	global_store_dwordx4 v166, v[36:39], s[14:15] offset:256 nt
	v_add_u32_e32 v200, 0xa0, v202
	v_mad_u32_u24 v166, v200, s30, v162
	v_pk_fma_f32 v[32:33], v[32:33], v[158:159], v[132:133] op_sel_hi:[1,0,1]
	v_pk_fma_f32 v[34:35], v[34:35], v[158:159], v[134:135] op_sel_hi:[1,0,1]
	v_pk_fma_f32 v[24:25], v[24:25], v[158:159], v[128:129] op_sel_hi:[1,0,1]
	v_pk_fma_f32 v[26:27], v[26:27], v[158:159], v[130:131] op_sel_hi:[1,0,1]
	v_cvt_pk_bf16_f32 v32, v32, v33
	v_cvt_pk_bf16_f32 v33, v34, v35
	v_cvt_pk_bf16_f32 v34, v24, v25
	v_cvt_pk_bf16_f32 v35, v26, v27
	global_store_dwordx4 v166, v[32:35], s[14:15] nt
	v_pk_fma_f32 v[20:21], v[20:21], v[158:159], v[140:141] op_sel_hi:[1,0,1]
	v_pk_fma_f32 v[22:23], v[22:23], v[158:159], v[142:143] op_sel_hi:[1,0,1]
	v_pk_fma_f32 v[12:13], v[12:13], v[158:159], v[136:137] op_sel_hi:[1,0,1]
	v_pk_fma_f32 v[14:15], v[14:15], v[158:159], v[138:139] op_sel_hi:[1,0,1]
	v_cvt_pk_bf16_f32 v20, v20, v21
	v_cvt_pk_bf16_f32 v21, v22, v23
	v_cvt_pk_bf16_f32 v22, v12, v13
	v_cvt_pk_bf16_f32 v23, v14, v15
	global_store_dwordx4 v166, v[20:23], s[14:15] offset:256 nt
	v_add_u32_e32 v200, 0xb0, v202
	v_mad_u32_u24 v166, v200, s30, v162
	v_pk_fma_f32 v[16:17], v[16:17], v[164:165], v[132:133] op_sel_hi:[1,0,1]
	v_pk_fma_f32 v[18:19], v[18:19], v[164:165], v[134:135] op_sel_hi:[1,0,1]
	v_pk_fma_f32 v[8:9], v[8:9], v[164:165], v[128:129] op_sel_hi:[1,0,1]
	v_pk_fma_f32 v[10:11], v[10:11], v[164:165], v[130:131] op_sel_hi:[1,0,1]
	v_cvt_pk_bf16_f32 v16, v16, v17
	v_cvt_pk_bf16_f32 v17, v18, v19
	v_cvt_pk_bf16_f32 v18, v8, v9
	v_cvt_pk_bf16_f32 v19, v10, v11
	global_store_dwordx4 v166, v[16:19], s[14:15] nt
	v_pk_fma_f32 v[4:5], v[4:5], v[164:165], v[140:141] op_sel_hi:[1,0,1]
	v_pk_fma_f32 v[6:7], v[6:7], v[164:165], v[142:143] op_sel_hi:[1,0,1]
	v_pk_fma_f32 v[0:1], v[0:1], v[164:165], v[136:137] op_sel_hi:[1,0,1]
	v_pk_fma_f32 v[2:3], v[2:3], v[164:165], v[138:139] op_sel_hi:[1,0,1]
	v_cvt_pk_bf16_f32 v4, v4, v5
	v_cvt_pk_bf16_f32 v5, v6, v7
	v_cvt_pk_bf16_f32 v6, v0, v1
	v_cvt_pk_bf16_f32 v7, v2, v3
	s_mov_b64 s[8:9], -1
	global_store_dwordx4 v166, v[4:7], s[14:15] offset:256 nt
	s_cbranch_vccnz .LBB0_356
	s_andn2_b64 vcc, exec, s[10:11]
	s_cbranch_vccnz .LBB0_355
	s_barrier
	s_branch .LBB0_355
